# compress unit K loop rewritten: fully unrolled, 14-step look-ahead ring of loads with counted vmcnt waits
# speedup vs baseline: 1.0005x; 1.0005x over previous
.LBB0_879:
	s_and_b64 vcc, exec, s[38:39]
	s_cbranch_vccz .LBB0_824
	s_bfe_u32 s44, s33, 0x10003
	s_lshl_b32 s38, s44, 7
	v_add_u32_e32 v2, s38, v146
	v_readlane_b32 s38, v254, 6
	v_readlane_b32 s39, v254, 7
	s_load_dwordx2 s[40:41], s[38:39], 0x50
	s_lshl_b32 s42, s44, 15
	v_ashrrev_i32_e32 v3, 31, v2
	s_load_dwordx2 s[38:39], s[38:39], 0xa0
	v_lshlrev_b64 v[50:51], 12, v[2:3]
	s_waitcnt lgkmcnt(0)
	s_add_u32 s40, s40, s42
	s_addc_u32 s41, s41, 0
	v_lshl_add_u64 v[2:3], v[88:89], 2, s[40:41]
	v_lshl_add_u64 v[4:5], v[90:91], 2, s[40:41]
	global_load_dwordx4 v[34:37], v[2:3], off
	global_load_dwordx4 v[38:41], v[4:5], off
	v_lshl_add_u64 v[2:3], v[92:93], 2, s[40:41]
	v_lshl_add_u64 v[4:5], v[94:95], 2, s[40:41]
	s_lshl_b32 s40, s33, 4
	s_ashr_i32 s42, s33, 5
	s_and_b32 s45, s40, 0x70
	v_or_b32_e32 v0, s45, v145
	s_lshl_b32 s40, s42, 11
	global_load_dwordx4 v[42:45], v[2:3], off
	global_load_dwordx4 v[46:49], v[4:5], off
	v_lshl_or_b32 v0, v0, 4, s40
	v_mov_b64_e32 v[2:3], s[38:39]
	s_movk_i32 s40, 0x600
	v_readlane_b32 s48, v254, 13
	s_bfe_u32 s43, s33, 0x10004
	v_mad_i64_i32 v[2:3], s[40:41], v0, s40, v[2:3]
	v_readlane_b32 s49, v254, 14
	s_lshl_b32 s40, s44, 8
	s_lshl_b32 s43, s43, 7
	s_mov_b32 s41, s49
	s_or_b32 s48, s43, s40
	v_writelane_b32 v254, s40, 13
	v_lshl_add_u64 v[2:3], v[2:3], 0, s[48:49]
	v_mov_b32_e32 v111, v1
	v_writelane_b32 v254, s41, 14
	s_mov_b64 s[40:41], 0x9600000
	v_lshl_add_u64 v[70:71], v[2:3], 0, s[40:41]
	v_lshl_add_u64 v[2:3], s[38:39], 0, v[50:51]
	v_lshl_add_u64 v[2:3], v[96:97], 1, v[2:3]
	s_mov_b64 s[40:41], 0x600000
	v_lshl_add_u64 v[4:5], v[98:99], 1, v[70:71]
	v_lshl_add_u64 v[22:23], v[2:3], 0, s[40:41]
	s_mov_b32 s40, 0x600000
	v_lshl_add_u64 v[18:19], v[102:103], 1, v[70:71]
	v_lshl_add_u64 v[10:11], v[4:5], 0, v[110:111]
	v_add_co_u32_e32 v2, vcc, s40, v2
	v_lshl_add_u64 v[4:5], v[100:101], 1, v[70:71]
	v_mov_b32_e32 v113, v1
	v_lshl_add_u64 v[24:25], v[18:19], 0, v[110:111]
	v_lshl_add_u64 v[18:19], v[104:105], 1, v[70:71]
	v_mov_b32_e32 v115, v1
	v_addc_co_u32_e32 v3, vcc, 0, v3, vcc
	v_lshl_add_u64 v[4:5], v[4:5], 0, v[112:113]
	v_lshl_add_u64 v[30:31], v[18:19], 0, v[114:115]
	v_lshl_add_u64 v[72:73], v[70:71], 0, v[110:111]
	v_lshl_add_u64 v[76:77], s[38:39], 0, v[108:109]
	v_lshl_add_u64 v[74:75], v[76:77], 0, v[50:51]
	s_mov_b64 s[48:49], 0xc00
	v_mov_b32_e32 v76, v72
	v_mov_b32_e32 v77, v73
	v_mov_b32_e32 v50, 0
	v_mov_b32_e32 v51, 0
	v_mov_b32_e32 v52, 0
	v_mov_b32_e32 v53, 0
	global_load_dwordx4 v[2:5], v[76:77], off
	global_load_dwordx4 v[6:9], v[74:75], off offset:-704
	global_load_dwordx4 v[10:13], v[76:77], off offset:64
	global_load_dwordx4 v[14:17], v[74:75], off offset:-640
	global_load_dwordx4 v[18:21], v[76:77], off offset:1536
	global_load_dwordx4 v[22:25], v[74:75], off offset:-576
	global_load_dwordx4 v[26:29], v[76:77], off offset:1600
	global_load_dwordx4 v[30:33], v[74:75], off offset:-512
	v_lshl_add_u64 v[76:77], v[76:77], 0, s[48:49]
	global_load_dwordx4 v[54:57], v[76:77], off
	global_load_dwordx4 v[58:61], v[74:75], off offset:-448
	global_load_dwordx4 v[62:65], v[76:77], off offset:64
	global_load_dwordx4 v[66:69], v[74:75], off offset:-384
	global_load_dwordx4 v[118:121], v[76:77], off offset:1536
	global_load_dwordx4 v[122:125], v[74:75], off offset:-320
	global_load_dwordx4 v[126:129], v[76:77], off offset:1600
	global_load_dwordx4 v[130:133], v[74:75], off offset:-256
	v_lshl_add_u64 v[76:77], v[76:77], 0, s[48:49]
	global_load_dwordx4 v[134:137], v[76:77], off
	global_load_dwordx4 v[192:195], v[74:75], off offset:-192
	global_load_dwordx4 v[196:199], v[76:77], off offset:64
	global_load_dwordx4 v[212:215], v[74:75], off offset:-128
	global_load_dwordx4 v[216:219], v[76:77], off offset:1536
	global_load_dwordx4 v[220:223], v[74:75], off offset:-64
	global_load_dwordx4 v[224:227], v[76:77], off offset:1600
	global_load_dwordx4 v[228:231], v[74:75], off
	v_lshl_add_u64 v[76:77], v[76:77], 0, s[48:49]
	global_load_dwordx4 v[232:235], v[76:77], off
	global_load_dwordx4 v[236:239], v[74:75], off offset:64
	global_load_dwordx4 v[240:243], v[76:77], off offset:64
	global_load_dwordx4 v[250:253], v[74:75], off offset:128
	s_waitcnt vmcnt(31)
	ds_write_b128 v161, v[34:37] offset:12416
	s_waitcnt vmcnt(30)
	ds_write_b128 v161, v[38:41] offset:20608
	s_waitcnt vmcnt(29)
	ds_write_b128 v161, v[42:45] offset:28800
	s_waitcnt vmcnt(28)
	ds_write_b128 v161, v[46:49] offset:36992
	s_waitcnt vmcnt(26)
	v_mfma_f32_16x16x32_bf16 v[50:53], v[2:5], v[6:9], v[50:53]
	global_load_dwordx4 v[2:5], v[76:77], off offset:1536
	global_load_dwordx4 v[6:9], v[74:75], off offset:192
	s_waitcnt vmcnt(26)
	v_mfma_f32_16x16x32_bf16 v[50:53], v[10:13], v[14:17], v[50:53]
	global_load_dwordx4 v[10:13], v[76:77], off offset:1600
	global_load_dwordx4 v[14:17], v[74:75], off offset:256
	s_waitcnt vmcnt(26)
	v_mfma_f32_16x16x32_bf16 v[50:53], v[18:21], v[22:25], v[50:53]
	v_lshl_add_u64 v[76:77], v[76:77], 0, s[48:49]
	global_load_dwordx4 v[18:21], v[76:77], off
	global_load_dwordx4 v[22:25], v[74:75], off offset:320
	s_waitcnt vmcnt(26)
	v_mfma_f32_16x16x32_bf16 v[50:53], v[26:29], v[30:33], v[50:53]
	global_load_dwordx4 v[26:29], v[76:77], off offset:64
	global_load_dwordx4 v[30:33], v[74:75], off offset:384
	s_waitcnt vmcnt(26)
	v_mfma_f32_16x16x32_bf16 v[50:53], v[54:57], v[58:61], v[50:53]
	global_load_dwordx4 v[54:57], v[76:77], off offset:1536
	global_load_dwordx4 v[58:61], v[74:75], off offset:448
	s_waitcnt vmcnt(26)
	v_mfma_f32_16x16x32_bf16 v[50:53], v[62:65], v[66:69], v[50:53]
	global_load_dwordx4 v[62:65], v[76:77], off offset:1600
	global_load_dwordx4 v[66:69], v[74:75], off offset:512
	s_waitcnt vmcnt(26)
	v_mfma_f32_16x16x32_bf16 v[50:53], v[118:121], v[122:125], v[50:53]
	v_lshl_add_u64 v[76:77], v[76:77], 0, s[48:49]
	global_load_dwordx4 v[118:121], v[76:77], off
	global_load_dwordx4 v[122:125], v[74:75], off offset:576
	s_waitcnt vmcnt(26)
	v_mfma_f32_16x16x32_bf16 v[50:53], v[126:129], v[130:133], v[50:53]
	global_load_dwordx4 v[126:129], v[76:77], off offset:64
	global_load_dwordx4 v[130:133], v[74:75], off offset:640
	s_waitcnt vmcnt(26)
	v_mfma_f32_16x16x32_bf16 v[50:53], v[134:137], v[192:195], v[50:53]
	global_load_dwordx4 v[134:137], v[76:77], off offset:1536
	global_load_dwordx4 v[192:195], v[74:75], off offset:704
	s_waitcnt vmcnt(26)
	v_mfma_f32_16x16x32_bf16 v[50:53], v[196:199], v[212:215], v[50:53]
	global_load_dwordx4 v[196:199], v[76:77], off offset:1600
	global_load_dwordx4 v[212:215], v[74:75], off offset:768
	s_waitcnt vmcnt(26)
	v_mfma_f32_16x16x32_bf16 v[50:53], v[216:219], v[220:223], v[50:53]
	v_lshl_add_u64 v[76:77], v[76:77], 0, s[48:49]
	global_load_dwordx4 v[216:219], v[76:77], off
	global_load_dwordx4 v[220:223], v[74:75], off offset:832
	s_waitcnt vmcnt(26)
	v_mfma_f32_16x16x32_bf16 v[50:53], v[224:227], v[228:231], v[50:53]
	global_load_dwordx4 v[224:227], v[76:77], off offset:64
	global_load_dwordx4 v[228:231], v[74:75], off offset:896
	s_waitcnt vmcnt(26)
	v_mfma_f32_16x16x32_bf16 v[50:53], v[232:235], v[236:239], v[50:53]
	global_load_dwordx4 v[232:235], v[76:77], off offset:1536
	global_load_dwordx4 v[236:239], v[74:75], off offset:960
	s_waitcnt vmcnt(26)
	v_mfma_f32_16x16x32_bf16 v[50:53], v[240:243], v[250:253], v[50:53]
	global_load_dwordx4 v[240:243], v[76:77], off offset:1600
	global_load_dwordx4 v[250:253], v[74:75], off offset:1024
	s_waitcnt vmcnt(26)
	v_mfma_f32_16x16x32_bf16 v[50:53], v[2:5], v[6:9], v[50:53]
	v_lshl_add_u64 v[76:77], v[76:77], 0, s[48:49]
	global_load_dwordx4 v[2:5], v[76:77], off
	global_load_dwordx4 v[6:9], v[74:75], off offset:1088
	s_waitcnt vmcnt(26)
	v_mfma_f32_16x16x32_bf16 v[50:53], v[10:13], v[14:17], v[50:53]
	global_load_dwordx4 v[10:13], v[76:77], off offset:64
	global_load_dwordx4 v[14:17], v[74:75], off offset:1152
	s_waitcnt vmcnt(26)
	v_mfma_f32_16x16x32_bf16 v[50:53], v[18:21], v[22:25], v[50:53]
	global_load_dwordx4 v[18:21], v[76:77], off offset:1536
	global_load_dwordx4 v[22:25], v[74:75], off offset:1216
	s_waitcnt vmcnt(26)
	v_mfma_f32_16x16x32_bf16 v[50:53], v[26:29], v[30:33], v[50:53]
	global_load_dwordx4 v[26:29], v[76:77], off offset:1600
	global_load_dwordx4 v[30:33], v[74:75], off offset:1280
	s_waitcnt vmcnt(26)
	v_mfma_f32_16x16x32_bf16 v[50:53], v[54:57], v[58:61], v[50:53]
	v_lshl_add_u64 v[76:77], v[76:77], 0, s[48:49]
	global_load_dwordx4 v[54:57], v[76:77], off
	global_load_dwordx4 v[58:61], v[74:75], off offset:1344
	s_waitcnt vmcnt(26)
	v_mfma_f32_16x16x32_bf16 v[50:53], v[62:65], v[66:69], v[50:53]
	global_load_dwordx4 v[62:65], v[76:77], off offset:64
	global_load_dwordx4 v[66:69], v[74:75], off offset:1408
	s_waitcnt vmcnt(26)
	v_mfma_f32_16x16x32_bf16 v[50:53], v[118:121], v[122:125], v[50:53]
	global_load_dwordx4 v[118:121], v[76:77], off offset:1536
	global_load_dwordx4 v[122:125], v[74:75], off offset:1472
	s_waitcnt vmcnt(26)
	v_mfma_f32_16x16x32_bf16 v[50:53], v[126:129], v[130:133], v[50:53]
	global_load_dwordx4 v[126:129], v[76:77], off offset:1600
	global_load_dwordx4 v[130:133], v[74:75], off offset:1536
	s_waitcnt vmcnt(26)
	v_mfma_f32_16x16x32_bf16 v[50:53], v[134:137], v[192:195], v[50:53]
	v_lshl_add_u64 v[76:77], v[76:77], 0, s[48:49]
	global_load_dwordx4 v[134:137], v[76:77], off
	global_load_dwordx4 v[192:195], v[74:75], off offset:1600
	s_waitcnt vmcnt(26)
	v_mfma_f32_16x16x32_bf16 v[50:53], v[196:199], v[212:215], v[50:53]
	global_load_dwordx4 v[196:199], v[76:77], off offset:64
	global_load_dwordx4 v[212:215], v[74:75], off offset:1664
	s_waitcnt vmcnt(26)
	v_mfma_f32_16x16x32_bf16 v[50:53], v[216:219], v[220:223], v[50:53]
	global_load_dwordx4 v[216:219], v[76:77], off offset:1536
	global_load_dwordx4 v[220:223], v[74:75], off offset:1728
	s_waitcnt vmcnt(26)
	v_mfma_f32_16x16x32_bf16 v[50:53], v[224:227], v[228:231], v[50:53]
	global_load_dwordx4 v[224:227], v[76:77], off offset:1600
	global_load_dwordx4 v[228:231], v[74:75], off offset:1792
	s_waitcnt vmcnt(26)
	v_mfma_f32_16x16x32_bf16 v[50:53], v[232:235], v[236:239], v[50:53]
	v_lshl_add_u64 v[76:77], v[76:77], 0, s[48:49]
	global_load_dwordx4 v[232:235], v[76:77], off
	global_load_dwordx4 v[236:239], v[74:75], off offset:1856
	s_waitcnt vmcnt(26)
	v_mfma_f32_16x16x32_bf16 v[50:53], v[240:243], v[250:253], v[50:53]
	global_load_dwordx4 v[240:243], v[76:77], off offset:64
	global_load_dwordx4 v[250:253], v[74:75], off offset:1920
	s_waitcnt vmcnt(26)
	v_mfma_f32_16x16x32_bf16 v[50:53], v[2:5], v[6:9], v[50:53]
	global_load_dwordx4 v[2:5], v[76:77], off offset:1536
	global_load_dwordx4 v[6:9], v[74:75], off offset:1984
	s_waitcnt vmcnt(26)
	v_mfma_f32_16x16x32_bf16 v[50:53], v[10:13], v[14:17], v[50:53]
	global_load_dwordx4 v[10:13], v[76:77], off offset:1600
	global_load_dwordx4 v[14:17], v[74:75], off offset:2048
	s_waitcnt vmcnt(26)
	v_mfma_f32_16x16x32_bf16 v[50:53], v[18:21], v[22:25], v[50:53]
	v_lshl_add_u64 v[76:77], v[76:77], 0, s[48:49]
	global_load_dwordx4 v[18:21], v[76:77], off
	global_load_dwordx4 v[22:25], v[74:75], off offset:2112
	s_waitcnt vmcnt(26)
	v_mfma_f32_16x16x32_bf16 v[50:53], v[26:29], v[30:33], v[50:53]
	global_load_dwordx4 v[26:29], v[76:77], off offset:64
	global_load_dwordx4 v[30:33], v[74:75], off offset:2176
	s_waitcnt vmcnt(26)
	v_mfma_f32_16x16x32_bf16 v[50:53], v[54:57], v[58:61], v[50:53]
	global_load_dwordx4 v[54:57], v[76:77], off offset:1536
	global_load_dwordx4 v[58:61], v[74:75], off offset:2240
	s_waitcnt vmcnt(26)
	v_mfma_f32_16x16x32_bf16 v[50:53], v[62:65], v[66:69], v[50:53]
	global_load_dwordx4 v[62:65], v[76:77], off offset:1600
	global_load_dwordx4 v[66:69], v[74:75], off offset:2304
	s_waitcnt vmcnt(26)
	v_mfma_f32_16x16x32_bf16 v[50:53], v[118:121], v[122:125], v[50:53]
	v_lshl_add_u64 v[76:77], v[76:77], 0, s[48:49]
	global_load_dwordx4 v[118:121], v[76:77], off
	global_load_dwordx4 v[122:125], v[74:75], off offset:2368
	s_waitcnt vmcnt(26)
	v_mfma_f32_16x16x32_bf16 v[50:53], v[126:129], v[130:133], v[50:53]
	global_load_dwordx4 v[126:129], v[76:77], off offset:64
	global_load_dwordx4 v[130:133], v[74:75], off offset:2432
	s_waitcnt vmcnt(26)
	v_mfma_f32_16x16x32_bf16 v[50:53], v[134:137], v[192:195], v[50:53]
	global_load_dwordx4 v[134:137], v[76:77], off offset:1536
	global_load_dwordx4 v[192:195], v[74:75], off offset:2496
	s_waitcnt vmcnt(26)
	v_mfma_f32_16x16x32_bf16 v[50:53], v[196:199], v[212:215], v[50:53]
	global_load_dwordx4 v[196:199], v[76:77], off offset:1600
	global_load_dwordx4 v[212:215], v[74:75], off offset:2560
	s_waitcnt vmcnt(26)
	v_mfma_f32_16x16x32_bf16 v[50:53], v[216:219], v[220:223], v[50:53]
	v_lshl_add_u64 v[76:77], v[76:77], 0, s[48:49]
	global_load_dwordx4 v[216:219], v[76:77], off
	global_load_dwordx4 v[220:223], v[74:75], off offset:2624
	s_waitcnt vmcnt(26)
	v_mfma_f32_16x16x32_bf16 v[50:53], v[224:227], v[228:231], v[50:53]
	global_load_dwordx4 v[224:227], v[76:77], off offset:64
	global_load_dwordx4 v[228:231], v[74:75], off offset:2688
	s_waitcnt vmcnt(26)
	v_mfma_f32_16x16x32_bf16 v[50:53], v[232:235], v[236:239], v[50:53]
	global_load_dwordx4 v[232:235], v[76:77], off offset:1536
	global_load_dwordx4 v[236:239], v[74:75], off offset:2752
	s_waitcnt vmcnt(26)
	v_mfma_f32_16x16x32_bf16 v[50:53], v[240:243], v[250:253], v[50:53]
	global_load_dwordx4 v[240:243], v[76:77], off offset:1600
	global_load_dwordx4 v[250:253], v[74:75], off offset:2816
	s_waitcnt vmcnt(26)
	v_mfma_f32_16x16x32_bf16 v[50:53], v[2:5], v[6:9], v[50:53]
	v_lshl_add_u64 v[76:77], v[76:77], 0, s[48:49]
	global_load_dwordx4 v[2:5], v[76:77], off
	global_load_dwordx4 v[6:9], v[74:75], off offset:2880
	s_waitcnt vmcnt(26)
	v_mfma_f32_16x16x32_bf16 v[50:53], v[10:13], v[14:17], v[50:53]
	global_load_dwordx4 v[10:13], v[76:77], off offset:64
	global_load_dwordx4 v[14:17], v[74:75], off offset:2944
	s_waitcnt vmcnt(26)
	v_mfma_f32_16x16x32_bf16 v[50:53], v[18:21], v[22:25], v[50:53]
	global_load_dwordx4 v[18:21], v[76:77], off offset:1536
	global_load_dwordx4 v[22:25], v[74:75], off offset:3008
	s_waitcnt vmcnt(26)
	v_mfma_f32_16x16x32_bf16 v[50:53], v[26:29], v[30:33], v[50:53]
	global_load_dwordx4 v[26:29], v[76:77], off offset:1600
	global_load_dwordx4 v[30:33], v[74:75], off offset:3072
	s_waitcnt vmcnt(26)
	v_mfma_f32_16x16x32_bf16 v[50:53], v[54:57], v[58:61], v[50:53]
	v_lshl_add_u64 v[76:77], v[76:77], 0, s[48:49]
	global_load_dwordx4 v[54:57], v[76:77], off
	global_load_dwordx4 v[58:61], v[74:75], off offset:3136
	s_waitcnt vmcnt(26)
	v_mfma_f32_16x16x32_bf16 v[50:53], v[62:65], v[66:69], v[50:53]
	global_load_dwordx4 v[62:65], v[76:77], off offset:64
	global_load_dwordx4 v[66:69], v[74:75], off offset:3200
	s_waitcnt vmcnt(26)
	v_mfma_f32_16x16x32_bf16 v[50:53], v[118:121], v[122:125], v[50:53]
	global_load_dwordx4 v[118:121], v[76:77], off offset:1536
	global_load_dwordx4 v[122:125], v[74:75], off offset:3264
	s_waitcnt vmcnt(26)
	v_mfma_f32_16x16x32_bf16 v[50:53], v[126:129], v[130:133], v[50:53]
	global_load_dwordx4 v[126:129], v[76:77], off offset:1600
	global_load_dwordx4 v[130:133], v[74:75], off offset:3328
	s_waitcnt vmcnt(26)
	v_mfma_f32_16x16x32_bf16 v[50:53], v[134:137], v[192:195], v[50:53]
	s_waitcnt vmcnt(24)
	v_mfma_f32_16x16x32_bf16 v[50:53], v[196:199], v[212:215], v[50:53]
	s_waitcnt vmcnt(22)
	v_mfma_f32_16x16x32_bf16 v[50:53], v[216:219], v[220:223], v[50:53]
	s_waitcnt vmcnt(20)
	v_mfma_f32_16x16x32_bf16 v[50:53], v[224:227], v[228:231], v[50:53]
	s_waitcnt vmcnt(18)
	v_mfma_f32_16x16x32_bf16 v[50:53], v[232:235], v[236:239], v[50:53]
	s_waitcnt vmcnt(16)
	v_mfma_f32_16x16x32_bf16 v[50:53], v[240:243], v[250:253], v[50:53]
	s_waitcnt vmcnt(14)
	v_mfma_f32_16x16x32_bf16 v[50:53], v[2:5], v[6:9], v[50:53]
	s_waitcnt vmcnt(12)
	v_mfma_f32_16x16x32_bf16 v[50:53], v[10:13], v[14:17], v[50:53]
	s_waitcnt vmcnt(10)
	v_mfma_f32_16x16x32_bf16 v[50:53], v[18:21], v[22:25], v[50:53]
	s_waitcnt vmcnt(8)
	v_mfma_f32_16x16x32_bf16 v[50:53], v[26:29], v[30:33], v[50:53]
	s_waitcnt vmcnt(6)
	v_mfma_f32_16x16x32_bf16 v[50:53], v[54:57], v[58:61], v[50:53]
	s_waitcnt vmcnt(4)
	v_mfma_f32_16x16x32_bf16 v[50:53], v[62:65], v[66:69], v[50:53]
	s_waitcnt vmcnt(2)
	v_mfma_f32_16x16x32_bf16 v[50:53], v[118:121], v[122:125], v[50:53]
	s_waitcnt vmcnt(0)
	v_mfma_f32_16x16x32_bf16 v[50:53], v[126:129], v[130:133], v[50:53]
	s_nop 0

.LBB0_2066:
	s_and_b64 vcc, exec, s[38:39]
	s_cbranch_vccz .LBB0_2011
	s_load_dwordx2 s[40:41], s[68:69], 0x50
	s_load_dwordx2 s[38:39], s[68:69], 0xa0
	s_bfe_u32 s44, s33, 0x10003
	s_or_b32 s46, s44, 2
	s_lshl_b32 s42, s46, 15
	s_waitcnt lgkmcnt(0)
	s_add_u32 s40, s40, s42
	s_addc_u32 s41, s41, 0
	v_lshl_add_u64 v[2:3], v[88:89], 2, s[40:41]
	v_lshl_add_u64 v[4:5], v[90:91], 2, s[40:41]
	global_load_dwordx4 v[34:37], v[2:3], off
	global_load_dwordx4 v[38:41], v[4:5], off
	v_lshl_add_u64 v[2:3], v[92:93], 2, s[40:41]
	v_lshl_add_u64 v[4:5], v[94:95], 2, s[40:41]
	s_lshl_b32 s40, s33, 4
	s_ashr_i32 s42, s33, 5
	s_and_b32 s45, s40, 0x70
	v_or_b32_e32 v0, s45, v145
	s_lshl_b32 s40, s42, 11
	global_load_dwordx4 v[42:45], v[2:3], off
	global_load_dwordx4 v[46:49], v[4:5], off
	v_lshl_or_b32 v0, v0, 4, s40
	v_mov_b64_e32 v[2:3], s[38:39]
	s_movk_i32 s40, 0x600
	v_readlane_b32 s48, v255, 32
	s_bfe_u32 s43, s33, 0x10004
	v_mad_i64_i32 v[2:3], s[40:41], v0, s40, v[2:3]
	v_readlane_b32 s49, v255, 33
	s_lshl_b32 s43, s43, 7
	s_lshl_b32 s40, s44, 8
	s_mov_b32 s41, s49
	s_or_b32 s48, s40, s43
	v_writelane_b32 v255, s40, 32
	v_lshl_add_u64 v[2:3], v[2:3], 0, s[48:49]
	v_mov_b32_e32 v111, v1
	v_writelane_b32 v255, s41, 33
	s_mov_b64 s[40:41], 0x9600000
	v_lshl_add_u64 v[70:71], v[2:3], 0, s[40:41]
	v_lshl_add_u32 v2, s46, 7, v146
	v_ashrrev_i32_e32 v3, 31, v2
	v_lshlrev_b64 v[2:3], 12, v[2:3]
	v_lshl_add_u64 v[2:3], s[38:39], 0, v[2:3]
	v_lshl_add_u64 v[2:3], v[96:97], 1, v[2:3]
	s_mov_b64 s[40:41], 0x600000
	v_lshl_add_u64 v[4:5], v[98:99], 1, v[70:71]
	v_lshl_add_u64 v[22:23], v[2:3], 0, s[40:41]
	s_mov_b32 s40, 0x600000
	v_lshl_add_u64 v[18:19], v[102:103], 1, v[70:71]
	v_lshl_add_u64 v[10:11], v[4:5], 0, v[110:111]
	v_add_co_u32_e32 v2, vcc, s40, v2
	v_lshl_add_u64 v[4:5], v[100:101], 1, v[70:71]
	v_mov_b32_e32 v113, v1
	v_lshl_add_u64 v[24:25], v[18:19], 0, v[110:111]
	v_lshl_add_u64 v[18:19], v[104:105], 1, v[70:71]
	v_mov_b32_e32 v115, v1
	v_addc_co_u32_e32 v3, vcc, 0, v3, vcc
	v_lshl_add_u64 v[4:5], v[4:5], 0, v[112:113]
	v_lshl_add_u64 v[30:31], v[18:19], 0, v[114:115]
	v_lshl_add_u32 v50, s44, 7, v158
	v_ashrrev_i32_e32 v51, 31, v50
	v_lshlrev_b64 v[50:51], 12, v[50:51]
	v_lshl_add_u64 v[72:73], v[70:71], 0, v[110:111]
	v_lshl_add_u64 v[76:77], s[38:39], 0, v[108:109]
	v_lshl_add_u64 v[74:75], v[76:77], 0, v[50:51]
	s_mov_b64 s[48:49], 0xc00
	v_mov_b32_e32 v76, v72
	v_mov_b32_e32 v77, v73
	v_mov_b32_e32 v50, 0
	v_mov_b32_e32 v51, 0
	v_mov_b32_e32 v52, 0
	v_mov_b32_e32 v53, 0
	global_load_dwordx4 v[2:5], v[76:77], off
	global_load_dwordx4 v[6:9], v[74:75], off offset:-704
	global_load_dwordx4 v[10:13], v[76:77], off offset:64
	global_load_dwordx4 v[14:17], v[74:75], off offset:-640
	global_load_dwordx4 v[18:21], v[76:77], off offset:1536
	global_load_dwordx4 v[22:25], v[74:75], off offset:-576
	global_load_dwordx4 v[26:29], v[76:77], off offset:1600
	global_load_dwordx4 v[30:33], v[74:75], off offset:-512
	v_lshl_add_u64 v[76:77], v[76:77], 0, s[48:49]
	global_load_dwordx4 v[54:57], v[76:77], off
	global_load_dwordx4 v[58:61], v[74:75], off offset:-448
	global_load_dwordx4 v[62:65], v[76:77], off offset:64
	global_load_dwordx4 v[66:69], v[74:75], off offset:-384
	global_load_dwordx4 v[118:121], v[76:77], off offset:1536
	global_load_dwordx4 v[122:125], v[74:75], off offset:-320
	global_load_dwordx4 v[126:129], v[76:77], off offset:1600
	global_load_dwordx4 v[130:133], v[74:75], off offset:-256
	v_lshl_add_u64 v[76:77], v[76:77], 0, s[48:49]
	global_load_dwordx4 v[134:137], v[76:77], off
	global_load_dwordx4 v[192:195], v[74:75], off offset:-192
	global_load_dwordx4 v[196:199], v[76:77], off offset:64
	global_load_dwordx4 v[212:215], v[74:75], off offset:-128
	global_load_dwordx4 v[216:219], v[76:77], off offset:1536
	global_load_dwordx4 v[220:223], v[74:75], off offset:-64
	global_load_dwordx4 v[224:227], v[76:77], off offset:1600
	global_load_dwordx4 v[228:231], v[74:75], off
	v_lshl_add_u64 v[76:77], v[76:77], 0, s[48:49]
	global_load_dwordx4 v[232:235], v[76:77], off
	global_load_dwordx4 v[236:239], v[74:75], off offset:64
	global_load_dwordx4 v[240:243], v[76:77], off offset:64
	global_load_dwordx4 v[250:253], v[74:75], off offset:128
	s_waitcnt vmcnt(31)
	ds_write_b128 v162, v[34:37] offset:12416
	s_waitcnt vmcnt(30)
	ds_write_b128 v162, v[38:41] offset:20608
	s_waitcnt vmcnt(29)
	ds_write_b128 v162, v[42:45] offset:28800
	s_waitcnt vmcnt(28)
	ds_write_b128 v162, v[46:49] offset:36992
	s_waitcnt vmcnt(26)
	v_mfma_f32_16x16x32_bf16 v[50:53], v[2:5], v[6:9], v[50:53]
	global_load_dwordx4 v[2:5], v[76:77], off offset:1536
	global_load_dwordx4 v[6:9], v[74:75], off offset:192
	s_waitcnt vmcnt(26)
	v_mfma_f32_16x16x32_bf16 v[50:53], v[10:13], v[14:17], v[50:53]
	global_load_dwordx4 v[10:13], v[76:77], off offset:1600
	global_load_dwordx4 v[14:17], v[74:75], off offset:256
	s_waitcnt vmcnt(26)
	v_mfma_f32_16x16x32_bf16 v[50:53], v[18:21], v[22:25], v[50:53]
	v_lshl_add_u64 v[76:77], v[76:77], 0, s[48:49]
	global_load_dwordx4 v[18:21], v[76:77], off
	global_load_dwordx4 v[22:25], v[74:75], off offset:320
	s_waitcnt vmcnt(26)
	v_mfma_f32_16x16x32_bf16 v[50:53], v[26:29], v[30:33], v[50:53]
	global_load_dwordx4 v[26:29], v[76:77], off offset:64
	global_load_dwordx4 v[30:33], v[74:75], off offset:384
	s_waitcnt vmcnt(26)
	v_mfma_f32_16x16x32_bf16 v[50:53], v[54:57], v[58:61], v[50:53]
	global_load_dwordx4 v[54:57], v[76:77], off offset:1536
	global_load_dwordx4 v[58:61], v[74:75], off offset:448
	s_waitcnt vmcnt(26)
	v_mfma_f32_16x16x32_bf16 v[50:53], v[62:65], v[66:69], v[50:53]
	global_load_dwordx4 v[62:65], v[76:77], off offset:1600
	global_load_dwordx4 v[66:69], v[74:75], off offset:512
	s_waitcnt vmcnt(26)
	v_mfma_f32_16x16x32_bf16 v[50:53], v[118:121], v[122:125], v[50:53]
	v_lshl_add_u64 v[76:77], v[76:77], 0, s[48:49]
	global_load_dwordx4 v[118:121], v[76:77], off
	global_load_dwordx4 v[122:125], v[74:75], off offset:576
	s_waitcnt vmcnt(26)
	v_mfma_f32_16x16x32_bf16 v[50:53], v[126:129], v[130:133], v[50:53]
	global_load_dwordx4 v[126:129], v[76:77], off offset:64
	global_load_dwordx4 v[130:133], v[74:75], off offset:640
	s_waitcnt vmcnt(26)
	v_mfma_f32_16x16x32_bf16 v[50:53], v[134:137], v[192:195], v[50:53]
	global_load_dwordx4 v[134:137], v[76:77], off offset:1536
	global_load_dwordx4 v[192:195], v[74:75], off offset:704
	s_waitcnt vmcnt(26)
	v_mfma_f32_16x16x32_bf16 v[50:53], v[196:199], v[212:215], v[50:53]
	global_load_dwordx4 v[196:199], v[76:77], off offset:1600
	global_load_dwordx4 v[212:215], v[74:75], off offset:768
	s_waitcnt vmcnt(26)
	v_mfma_f32_16x16x32_bf16 v[50:53], v[216:219], v[220:223], v[50:53]
	v_lshl_add_u64 v[76:77], v[76:77], 0, s[48:49]
	global_load_dwordx4 v[216:219], v[76:77], off
	global_load_dwordx4 v[220:223], v[74:75], off offset:832
	s_waitcnt vmcnt(26)
	v_mfma_f32_16x16x32_bf16 v[50:53], v[224:227], v[228:231], v[50:53]
	global_load_dwordx4 v[224:227], v[76:77], off offset:64
	global_load_dwordx4 v[228:231], v[74:75], off offset:896
	s_waitcnt vmcnt(26)
	v_mfma_f32_16x16x32_bf16 v[50:53], v[232:235], v[236:239], v[50:53]
	global_load_dwordx4 v[232:235], v[76:77], off offset:1536
	global_load_dwordx4 v[236:239], v[74:75], off offset:960
	s_waitcnt vmcnt(26)
	v_mfma_f32_16x16x32_bf16 v[50:53], v[240:243], v[250:253], v[50:53]
	global_load_dwordx4 v[240:243], v[76:77], off offset:1600
	global_load_dwordx4 v[250:253], v[74:75], off offset:1024
	s_waitcnt vmcnt(26)
	v_mfma_f32_16x16x32_bf16 v[50:53], v[2:5], v[6:9], v[50:53]
	v_lshl_add_u64 v[76:77], v[76:77], 0, s[48:49]
	global_load_dwordx4 v[2:5], v[76:77], off
	global_load_dwordx4 v[6:9], v[74:75], off offset:1088
	s_waitcnt vmcnt(26)
	v_mfma_f32_16x16x32_bf16 v[50:53], v[10:13], v[14:17], v[50:53]
	global_load_dwordx4 v[10:13], v[76:77], off offset:64
	global_load_dwordx4 v[14:17], v[74:75], off offset:1152
	s_waitcnt vmcnt(26)
	v_mfma_f32_16x16x32_bf16 v[50:53], v[18:21], v[22:25], v[50:53]
	global_load_dwordx4 v[18:21], v[76:77], off offset:1536
	global_load_dwordx4 v[22:25], v[74:75], off offset:1216
	s_waitcnt vmcnt(26)
	v_mfma_f32_16x16x32_bf16 v[50:53], v[26:29], v[30:33], v[50:53]
	global_load_dwordx4 v[26:29], v[76:77], off offset:1600
	global_load_dwordx4 v[30:33], v[74:75], off offset:1280
	s_waitcnt vmcnt(26)
	v_mfma_f32_16x16x32_bf16 v[50:53], v[54:57], v[58:61], v[50:53]
	v_lshl_add_u64 v[76:77], v[76:77], 0, s[48:49]
	global_load_dwordx4 v[54:57], v[76:77], off
	global_load_dwordx4 v[58:61], v[74:75], off offset:1344
	s_waitcnt vmcnt(26)
	v_mfma_f32_16x16x32_bf16 v[50:53], v[62:65], v[66:69], v[50:53]
	global_load_dwordx4 v[62:65], v[76:77], off offset:64
	global_load_dwordx4 v[66:69], v[74:75], off offset:1408
	s_waitcnt vmcnt(26)
	v_mfma_f32_16x16x32_bf16 v[50:53], v[118:121], v[122:125], v[50:53]
	global_load_dwordx4 v[118:121], v[76:77], off offset:1536
	global_load_dwordx4 v[122:125], v[74:75], off offset:1472
	s_waitcnt vmcnt(26)
	v_mfma_f32_16x16x32_bf16 v[50:53], v[126:129], v[130:133], v[50:53]
	global_load_dwordx4 v[126:129], v[76:77], off offset:1600
	global_load_dwordx4 v[130:133], v[74:75], off offset:1536
	s_waitcnt vmcnt(26)
	v_mfma_f32_16x16x32_bf16 v[50:53], v[134:137], v[192:195], v[50:53]
	v_lshl_add_u64 v[76:77], v[76:77], 0, s[48:49]
	global_load_dwordx4 v[134:137], v[76:77], off
	global_load_dwordx4 v[192:195], v[74:75], off offset:1600
	s_waitcnt vmcnt(26)
	v_mfma_f32_16x16x32_bf16 v[50:53], v[196:199], v[212:215], v[50:53]
	global_load_dwordx4 v[196:199], v[76:77], off offset:64
	global_load_dwordx4 v[212:215], v[74:75], off offset:1664
	s_waitcnt vmcnt(26)
	v_mfma_f32_16x16x32_bf16 v[50:53], v[216:219], v[220:223], v[50:53]
	global_load_dwordx4 v[216:219], v[76:77], off offset:1536
	global_load_dwordx4 v[220:223], v[74:75], off offset:1728
	s_waitcnt vmcnt(26)
	v_mfma_f32_16x16x32_bf16 v[50:53], v[224:227], v[228:231], v[50:53]
	global_load_dwordx4 v[224:227], v[76:77], off offset:1600
	global_load_dwordx4 v[228:231], v[74:75], off offset:1792
	s_waitcnt vmcnt(26)
	v_mfma_f32_16x16x32_bf16 v[50:53], v[232:235], v[236:239], v[50:53]
	v_lshl_add_u64 v[76:77], v[76:77], 0, s[48:49]
	global_load_dwordx4 v[232:235], v[76:77], off
	global_load_dwordx4 v[236:239], v[74:75], off offset:1856
	s_waitcnt vmcnt(26)
	v_mfma_f32_16x16x32_bf16 v[50:53], v[240:243], v[250:253], v[50:53]
	global_load_dwordx4 v[240:243], v[76:77], off offset:64
	global_load_dwordx4 v[250:253], v[74:75], off offset:1920
	s_waitcnt vmcnt(26)
	v_mfma_f32_16x16x32_bf16 v[50:53], v[2:5], v[6:9], v[50:53]
	global_load_dwordx4 v[2:5], v[76:77], off offset:1536
	global_load_dwordx4 v[6:9], v[74:75], off offset:1984
	s_waitcnt vmcnt(26)
	v_mfma_f32_16x16x32_bf16 v[50:53], v[10:13], v[14:17], v[50:53]
	global_load_dwordx4 v[10:13], v[76:77], off offset:1600
	global_load_dwordx4 v[14:17], v[74:75], off offset:2048
	s_waitcnt vmcnt(26)
	v_mfma_f32_16x16x32_bf16 v[50:53], v[18:21], v[22:25], v[50:53]
	v_lshl_add_u64 v[76:77], v[76:77], 0, s[48:49]
	global_load_dwordx4 v[18:21], v[76:77], off
	global_load_dwordx4 v[22:25], v[74:75], off offset:2112
	s_waitcnt vmcnt(26)
	v_mfma_f32_16x16x32_bf16 v[50:53], v[26:29], v[30:33], v[50:53]
	global_load_dwordx4 v[26:29], v[76:77], off offset:64
	global_load_dwordx4 v[30:33], v[74:75], off offset:2176
	s_waitcnt vmcnt(26)
	v_mfma_f32_16x16x32_bf16 v[50:53], v[54:57], v[58:61], v[50:53]
	global_load_dwordx4 v[54:57], v[76:77], off offset:1536
	global_load_dwordx4 v[58:61], v[74:75], off offset:2240
	s_waitcnt vmcnt(26)
	v_mfma_f32_16x16x32_bf16 v[50:53], v[62:65], v[66:69], v[50:53]
	global_load_dwordx4 v[62:65], v[76:77], off offset:1600
	global_load_dwordx4 v[66:69], v[74:75], off offset:2304
	s_waitcnt vmcnt(26)
	v_mfma_f32_16x16x32_bf16 v[50:53], v[118:121], v[122:125], v[50:53]
	v_lshl_add_u64 v[76:77], v[76:77], 0, s[48:49]
	global_load_dwordx4 v[118:121], v[76:77], off
	global_load_dwordx4 v[122:125], v[74:75], off offset:2368
	s_waitcnt vmcnt(26)
	v_mfma_f32_16x16x32_bf16 v[50:53], v[126:129], v[130:133], v[50:53]
	global_load_dwordx4 v[126:129], v[76:77], off offset:64
	global_load_dwordx4 v[130:133], v[74:75], off offset:2432
	s_waitcnt vmcnt(26)
	v_mfma_f32_16x16x32_bf16 v[50:53], v[134:137], v[192:195], v[50:53]
	global_load_dwordx4 v[134:137], v[76:77], off offset:1536
	global_load_dwordx4 v[192:195], v[74:75], off offset:2496
	s_waitcnt vmcnt(26)
	v_mfma_f32_16x16x32_bf16 v[50:53], v[196:199], v[212:215], v[50:53]
	global_load_dwordx4 v[196:199], v[76:77], off offset:1600
	global_load_dwordx4 v[212:215], v[74:75], off offset:2560
	s_waitcnt vmcnt(26)
	v_mfma_f32_16x16x32_bf16 v[50:53], v[216:219], v[220:223], v[50:53]
	v_lshl_add_u64 v[76:77], v[76:77], 0, s[48:49]
	global_load_dwordx4 v[216:219], v[76:77], off
	global_load_dwordx4 v[220:223], v[74:75], off offset:2624
	s_waitcnt vmcnt(26)
	v_mfma_f32_16x16x32_bf16 v[50:53], v[224:227], v[228:231], v[50:53]
	global_load_dwordx4 v[224:227], v[76:77], off offset:64
	global_load_dwordx4 v[228:231], v[74:75], off offset:2688
	s_waitcnt vmcnt(26)
	v_mfma_f32_16x16x32_bf16 v[50:53], v[232:235], v[236:239], v[50:53]
	global_load_dwordx4 v[232:235], v[76:77], off offset:1536
	global_load_dwordx4 v[236:239], v[74:75], off offset:2752
	s_waitcnt vmcnt(26)
	v_mfma_f32_16x16x32_bf16 v[50:53], v[240:243], v[250:253], v[50:53]
	global_load_dwordx4 v[240:243], v[76:77], off offset:1600
	global_load_dwordx4 v[250:253], v[74:75], off offset:2816
	s_waitcnt vmcnt(26)
	v_mfma_f32_16x16x32_bf16 v[50:53], v[2:5], v[6:9], v[50:53]
	v_lshl_add_u64 v[76:77], v[76:77], 0, s[48:49]
	global_load_dwordx4 v[2:5], v[76:77], off
	global_load_dwordx4 v[6:9], v[74:75], off offset:2880
	s_waitcnt vmcnt(26)
	v_mfma_f32_16x16x32_bf16 v[50:53], v[10:13], v[14:17], v[50:53]
	global_load_dwordx4 v[10:13], v[76:77], off offset:64
	global_load_dwordx4 v[14:17], v[74:75], off offset:2944
	s_waitcnt vmcnt(26)
	v_mfma_f32_16x16x32_bf16 v[50:53], v[18:21], v[22:25], v[50:53]
	global_load_dwordx4 v[18:21], v[76:77], off offset:1536
	global_load_dwordx4 v[22:25], v[74:75], off offset:3008
	s_waitcnt vmcnt(26)
	v_mfma_f32_16x16x32_bf16 v[50:53], v[26:29], v[30:33], v[50:53]
	global_load_dwordx4 v[26:29], v[76:77], off offset:1600
	global_load_dwordx4 v[30:33], v[74:75], off offset:3072
	s_waitcnt vmcnt(26)
	v_mfma_f32_16x16x32_bf16 v[50:53], v[54:57], v[58:61], v[50:53]
	v_lshl_add_u64 v[76:77], v[76:77], 0, s[48:49]
	global_load_dwordx4 v[54:57], v[76:77], off
	global_load_dwordx4 v[58:61], v[74:75], off offset:3136
	s_waitcnt vmcnt(26)
	v_mfma_f32_16x16x32_bf16 v[50:53], v[62:65], v[66:69], v[50:53]
	global_load_dwordx4 v[62:65], v[76:77], off offset:64
	global_load_dwordx4 v[66:69], v[74:75], off offset:3200
	s_waitcnt vmcnt(26)
	v_mfma_f32_16x16x32_bf16 v[50:53], v[118:121], v[122:125], v[50:53]
	global_load_dwordx4 v[118:121], v[76:77], off offset:1536
	global_load_dwordx4 v[122:125], v[74:75], off offset:3264
	s_waitcnt vmcnt(26)
	v_mfma_f32_16x16x32_bf16 v[50:53], v[126:129], v[130:133], v[50:53]
	global_load_dwordx4 v[126:129], v[76:77], off offset:1600
	global_load_dwordx4 v[130:133], v[74:75], off offset:3328
	s_waitcnt vmcnt(26)
	v_mfma_f32_16x16x32_bf16 v[50:53], v[134:137], v[192:195], v[50:53]
	s_waitcnt vmcnt(24)
	v_mfma_f32_16x16x32_bf16 v[50:53], v[196:199], v[212:215], v[50:53]
	s_waitcnt vmcnt(22)
	v_mfma_f32_16x16x32_bf16 v[50:53], v[216:219], v[220:223], v[50:53]
	s_waitcnt vmcnt(20)
	v_mfma_f32_16x16x32_bf16 v[50:53], v[224:227], v[228:231], v[50:53]
	s_waitcnt vmcnt(18)
	v_mfma_f32_16x16x32_bf16 v[50:53], v[232:235], v[236:239], v[50:53]
	s_waitcnt vmcnt(16)
	v_mfma_f32_16x16x32_bf16 v[50:53], v[240:243], v[250:253], v[50:53]
	s_waitcnt vmcnt(14)
	v_mfma_f32_16x16x32_bf16 v[50:53], v[2:5], v[6:9], v[50:53]
	s_waitcnt vmcnt(12)
	v_mfma_f32_16x16x32_bf16 v[50:53], v[10:13], v[14:17], v[50:53]
	s_waitcnt vmcnt(10)
	v_mfma_f32_16x16x32_bf16 v[50:53], v[18:21], v[22:25], v[50:53]
	s_waitcnt vmcnt(8)
	v_mfma_f32_16x16x32_bf16 v[50:53], v[26:29], v[30:33], v[50:53]
	s_waitcnt vmcnt(6)
	v_mfma_f32_16x16x32_bf16 v[50:53], v[54:57], v[58:61], v[50:53]
	s_waitcnt vmcnt(4)
	v_mfma_f32_16x16x32_bf16 v[50:53], v[62:65], v[66:69], v[50:53]
	s_waitcnt vmcnt(2)
	v_mfma_f32_16x16x32_bf16 v[50:53], v[118:121], v[122:125], v[50:53]
	s_waitcnt vmcnt(0)
	v_mfma_f32_16x16x32_bf16 v[50:53], v[126:129], v[130:133], v[50:53]
	s_nop 0
